# MLA loop: K/V LDS stores moved from the end of the iteration into the MFMA section (after the vmcnt wait at ~60% of the tile) so the store burst overlaps compute
# speedup vs baseline: 1.0406x; 1.0133x over previous
;     ...
;                 if (MODE == 0 && (64 * kt + 63 > q0 + 32 * w)) {
; #pragma unroll
;                     for (int mt = 0; mt < 2; ++mt)
; #pragma unroll
;                         for (int qd = 0; qd < 4; ++qd)
; #pragma unroll
;                             for (int e = 0; e < 4; ++e)
;                                 if (64 * kt + 32 * mt + 8 * qd + 4 * h + e > qidx) s4[mt][qd][e] = -INFINITY;
;                 }
.Lm3_even_nok:
	s_waitcnt lgkmcnt(0)
	s_barrier
	s_cmp_lt_u32 s17, s66
	s_cselect_b64 s[24:25], -1, 0
	ds_read_b128 v[208:211], v216 offset:22784
	ds_read_b128 v[232:235], v216 offset:29440
	ds_read_b128 v[236:239], v216 offset:22816
	ds_read_b128 v[240:243], v216 offset:29472
	ds_read_b128 v[244:247], v216 offset:22848
	ds_read_b128 v[248:251], v216 offset:29504
	s_add_i32 s14, s16, 63
	v_cmp_gt_i32_e32 vcc, s14, v125
	s_and_saveexec_b64 s[14:15], vcc
	s_cbranch_execz .Lm3_nomask_e
	v_sub_u32_e32 v213, v126, v123
	v_subrev_u32_e32 v213, s16, v213
	v_cmp_le_i32_e32 vcc, 0, v213
	s_nop 1
	v_cndmask_b32_e32 v50, v228, v50, vcc
	v_cmp_le_i32_e32 vcc, 1, v213
	s_nop 1
	v_cndmask_b32_e32 v51, v228, v51, vcc
	v_cmp_le_i32_e32 vcc, 2, v213
	s_nop 1
	v_cndmask_b32_e32 v52, v228, v52, vcc
	v_cmp_le_i32_e32 vcc, 3, v213
	s_nop 1
	v_cndmask_b32_e32 v53, v228, v53, vcc
	v_cmp_le_i32_e32 vcc, 8, v213
	s_nop 1
	v_cndmask_b32_e32 v54, v228, v54, vcc
	v_cmp_le_i32_e32 vcc, 9, v213
	s_nop 1
	v_cndmask_b32_e32 v55, v228, v55, vcc
	v_cmp_le_i32_e32 vcc, 10, v213
	s_nop 1
	v_cndmask_b32_e32 v56, v228, v56, vcc
	v_cmp_le_i32_e32 vcc, 11, v213
	s_nop 1
	v_cndmask_b32_e32 v57, v228, v57, vcc
	v_cmp_le_i32_e32 vcc, 16, v213
	s_nop 1
	v_cndmask_b32_e32 v58, v228, v58, vcc
	v_cmp_le_i32_e32 vcc, 17, v213
	s_nop 1
	v_cndmask_b32_e32 v59, v228, v59, vcc
	v_cmp_le_i32_e32 vcc, 18, v213
	s_nop 1
	v_cndmask_b32_e32 v60, v228, v60, vcc
	v_cmp_le_i32_e32 vcc, 19, v213
	s_nop 1
	v_cndmask_b32_e32 v61, v228, v61, vcc
	v_cmp_le_i32_e32 vcc, 24, v213
	s_nop 1
	v_cndmask_b32_e32 v62, v228, v62, vcc
	v_cmp_le_i32_e32 vcc, 25, v213
	s_nop 1
	v_cndmask_b32_e32 v63, v228, v63, vcc
	v_cmp_le_i32_e32 vcc, 26, v213
	s_nop 1
	v_cndmask_b32_e32 v64, v228, v64, vcc
	v_cmp_le_i32_e32 vcc, 27, v213
	s_nop 1
	v_cndmask_b32_e32 v65, v228, v65, vcc
	v_cmp_le_i32_e32 vcc, 32, v213
	s_nop 1
	v_cndmask_b32_e32 v34, v228, v34, vcc
	v_cmp_le_i32_e32 vcc, 33, v213
	s_nop 1
	v_cndmask_b32_e32 v35, v228, v35, vcc
	v_cmp_le_i32_e32 vcc, 34, v213
	s_nop 1
	v_cndmask_b32_e32 v36, v228, v36, vcc
	v_cmp_le_i32_e32 vcc, 35, v213
	s_nop 1
	v_cndmask_b32_e32 v37, v228, v37, vcc
	v_cmp_le_i32_e32 vcc, 40, v213
	s_nop 1
	v_cndmask_b32_e32 v38, v228, v38, vcc
	v_cmp_le_i32_e32 vcc, 41, v213
	s_nop 1
	v_cndmask_b32_e32 v39, v228, v39, vcc
	v_cmp_le_i32_e32 vcc, 42, v213
	s_nop 1
	v_cndmask_b32_e32 v40, v228, v40, vcc
	v_cmp_le_i32_e32 vcc, 43, v213
	s_nop 1
	v_cndmask_b32_e32 v41, v228, v41, vcc
	v_cmp_le_i32_e32 vcc, 48, v213
	s_nop 1
	v_cndmask_b32_e32 v42, v228, v42, vcc
	v_cmp_le_i32_e32 vcc, 49, v213
	s_nop 1
	v_cndmask_b32_e32 v43, v228, v43, vcc
	v_cmp_le_i32_e32 vcc, 50, v213
	s_nop 1
	v_cndmask_b32_e32 v44, v228, v44, vcc
	v_cmp_le_i32_e32 vcc, 51, v213
	s_nop 1
	v_cndmask_b32_e32 v45, v228, v45, vcc
	v_cmp_le_i32_e32 vcc, 56, v213
	s_nop 1
	v_cndmask_b32_e32 v46, v228, v46, vcc
	v_cmp_le_i32_e32 vcc, 57, v213
	s_nop 1
	v_cndmask_b32_e32 v47, v228, v47, vcc
	v_cmp_le_i32_e32 vcc, 58, v213
	s_nop 1
	v_cndmask_b32_e32 v48, v228, v48, vcc
	v_cmp_le_i32_e32 vcc, 59, v213
	s_nop 1
	v_cndmask_b32_e32 v49, v228, v49, vcc

;     ...
;     auto st_tile = [&](int buf) {
;         bf16_t* sK = (bf16_t*)(smem + buf * ATT_BUF); bf16_t* sV = (bf16_t*)(smem + buf * ATT_BUF + 13312); float* sC = (float*)(smem + buf * ATT_BUF + 22528);
; #pragma unroll
;     ...
;                 float mx = fmaxf(s4[0][0].x, s4[1][0].x);
; #pragma unroll
;                 for (int qd = 0; qd < 4; ++qd) {
;                     mx = fmaxf(fmaxf(mx, s4[0][qd].y), s4[1][qd].y);
;                     mx = fmaxf(fmaxf(mx, s4[0][qd].z), s4[1][qd].z);
;                     mx = fmaxf(fmaxf(mx, s4[0][qd].w), s4[1][qd].w);
;                     if (qd < 3) mx = fmaxf(fmaxf(mx, s4[0][qd + 1].x), s4[1][qd + 1].x);
;                 }
;                 mx = xhalf_max(mx);
;                 const float mn = fmaxf(m, mx), alpha = fexp2(m - mn);
;                 m = mn;
;                 f32x4 ps4 = {0.f, 0.f, 0.f, 0.f};
;                 const float nmn = -mn;
;                 const f32x4 nm4 = {nmn, nmn, nmn, nmn};
;                 if (__builtin_amdgcn_ballot_w64(alpha != 1.f) != 0) { o0 *= alpha; o1 *= alpha; }
; #pragma unroll
;                 for (int s2 = 0; s2 < 4; ++s2) {
;                     const int mt = s2 >> 1, s = s2 & 1;
;                     f32x4 da = s4[mt][2 * s] + nm4, db = s4[mt][2 * s + 1] + nm4;
;                     da.x = fexp2(da.x); da.y = fexp2(da.y); da.z = fexp2(da.z); da.w = fexp2(da.w);
;                     db.x = fexp2(db.x); db.y = fexp2(db.y); db.z = fexp2(db.z); db.w = fexp2(db.w);
;                     ps4 += da; ps4 += db;
;                     u32x4 pp;
;                     pp.x = pk2(da.x, da.y); pp.y = pk2(da.z, da.w); pp.z = pk2(db.x, db.y); pp.w = pk2(db.z, db.w);
;                     const bf16x8 pfr = __builtin_bit_cast(bf16x8, pp);
;                     const s16x4 a0 = *(const s16x4*)(sV + r * LS + 16 * s2 + 4 * h), a1 = *(const s16x4*)(sV + r * LS + 16 * s2 + 8 + 4 * h);
;                     const s16x4 b0 = *(const s16x4*)(sV + (32 + r) * LS + 16 * s2 + 4 * h), b1 = *(const s16x4*)(sV + (32 + r) * LS + 16 * s2 + 8 + 4 * h);
;                     const bf16x8 v0 = __builtin_shufflevector(a0, a1, 0, 1, 2, 3, 4, 5, 6, 7), v1 = __builtin_shufflevector(b0, b1, 0, 1, 2, 3, 4, 5, 6, 7);
;                     o0 = MFMA32(v0, pfr, o0);
;                     o1 = MFMA32(v1, pfr, o1);
;                 }
;                 lsum = lsum * alpha + ((ps4.x + ps4.y) + (ps4.z + ps4.w));
.Lm3_back_e:
	s_waitcnt lgkmcnt(4)
	v_mfma_f32_32x32x16_bf16 v[176:191], v[208:211], v[86:89], v[156:171]
	v_exp_f32_e32 v50, v50
	v_exp_f32_e32 v51, v51
	v_exp_f32_e32 v52, v52
	v_mfma_f32_32x32x16_bf16 v[192:207], v[232:235], v[86:89], v[156:171]
	ds_read_b128 v[208:211], v216 offset:22880
	ds_read_b128 v[232:235], v216 offset:29536
	v_exp_f32_e32 v53, v53
	v_exp_f32_e32 v54, v54
	v_exp_f32_e32 v55, v55
	s_waitcnt lgkmcnt(4)
	v_mfma_f32_32x32x16_bf16 v[176:191], v[236:239], v[90:93], v[176:191]
	v_exp_f32_e32 v56, v56
	v_exp_f32_e32 v57, v57
	v_cvt_pk_bf16_f32 v142, v50, v51
	v_mfma_f32_32x32x16_bf16 v[192:207], v[240:243], v[90:93], v[192:207]
	ds_read_b128 v[236:239], v231 offset:13312
	ds_read_b128 v[240:243], v231 offset:17920
	v_cvt_pk_bf16_f32 v143, v52, v53
	v_cvt_pk_bf16_f32 v144, v54, v55
	v_cvt_pk_bf16_f32 v145, v56, v57
	v_exp_f32_e32 v58, v58
	s_waitcnt lgkmcnt(4)
	v_mfma_f32_32x32x16_bf16 v[176:191], v[244:247], v[94:97], v[176:191]
	v_exp_f32_e32 v59, v59
	v_exp_f32_e32 v60, v60
	v_exp_f32_e32 v61, v61
	v_mfma_f32_32x32x16_bf16 v[192:207], v[248:251], v[94:97], v[192:207]
	ds_read_b128 v[244:247], v216 offset:22912
	ds_read_b128 v[248:251], v216 offset:29568
	v_exp_f32_e32 v62, v62
	v_exp_f32_e32 v63, v63
	v_exp_f32_e32 v64, v64
	s_waitcnt lgkmcnt(4)
	v_mfma_f32_32x32x16_bf16 v[176:191], v[208:211], v[98:101], v[176:191]
	v_exp_f32_e32 v65, v65
	v_cvt_pk_bf16_f32 v146, v58, v59
	v_cvt_pk_bf16_f32 v147, v60, v61
	v_cvt_pk_bf16_f32 v148, v62, v63
	v_mfma_f32_32x32x16_bf16 v[192:207], v[232:235], v[98:101], v[192:207]
	ds_read_b128 v[208:211], v231 offset:13344
	ds_read_b128 v[232:235], v231 offset:17952
	v_cvt_pk_bf16_f32 v149, v64, v65
	v_exp_f32_e32 v34, v34
	v_exp_f32_e32 v35, v35
	s_waitcnt lgkmcnt(4)
	v_mfma_f32_32x32x16_bf16 v[18:33], v[236:239], v[142:145], v[18:33]
	v_exp_f32_e32 v36, v36
	v_exp_f32_e32 v37, v37
	v_exp_f32_e32 v38, v38
	v_mfma_f32_32x32x16_bf16 v[2:17], v[240:243], v[142:145], v[2:17]
	ds_read_b128 v[236:239], v216 offset:22944
	ds_read_b128 v[240:243], v216 offset:29600
	v_exp_f32_e32 v39, v39
	v_exp_f32_e32 v40, v40
	v_exp_f32_e32 v41, v41
	s_waitcnt lgkmcnt(4)
	v_mfma_f32_32x32x16_bf16 v[176:191], v[244:247], v[102:105], v[176:191]
	v_cvt_pk_bf16_f32 v150, v34, v35
	v_cvt_pk_bf16_f32 v151, v36, v37
	v_cvt_pk_bf16_f32 v152, v38, v39
	v_cvt_pk_bf16_f32 v153, v40, v41
	v_exp_f32_e32 v42, v42
	v_mfma_f32_32x32x16_bf16 v[192:207], v[248:251], v[102:105], v[192:207]
	s_waitcnt vmcnt(0)
	ds_write2_b64 v138, v[78:79], v[80:81] offset1:2
	ds_read_b128 v[244:247], v231 offset:13376
	ds_read_b128 v[248:251], v231 offset:17984
	v_exp_f32_e32 v43, v43
	v_exp_f32_e32 v44, v44
	v_exp_f32_e32 v45, v45
	s_waitcnt lgkmcnt(5)
	v_mfma_f32_32x32x16_bf16 v[18:33], v[208:211], v[146:149], v[18:33]
	ds_write2_b64 v139, v[82:83], v[84:85] offset1:2
	v_exp_f32_e32 v46, v46
	v_exp_f32_e32 v47, v47
	v_mfma_f32_32x32x16_bf16 v[2:17], v[232:235], v[146:149], v[2:17]
	ds_read_b128 v[208:211], v231 offset:13408
	ds_read_b128 v[232:235], v231 offset:18016
	v_exp_f32_e32 v48, v48
	v_exp_f32_e32 v49, v49
	v_cvt_pk_bf16_f32 v142, v42, v43
	v_cvt_pk_bf16_f32 v143, v44, v45
	s_waitcnt lgkmcnt(6)
	v_mfma_f32_32x32x16_bf16 v[176:191], v[236:239], v[106:109], v[176:191]
	s_mov_b64 exec, s[24:25]
	ds_write_b128 v127, v[66:69]
	ds_write_b128 v128, v[70:73]
	ds_write_b128 v129, v[74:77]
	s_mov_b64 exec, -1
	v_cvt_pk_bf16_f32 v144, v46, v47
	v_cvt_pk_bf16_f32 v145, v48, v49
	v_add_f32_e32 v141, v50, v51
	v_add_f32_e32 v154, v52, v53
	v_add_f32_e32 v212, v54, v55
	v_add_f32_e32 v213, v56, v57
	v_mfma_f32_32x32x16_bf16 v[192:207], v[240:243], v[106:109], v[192:207]
	v_add_f32_e32 v141, v141, v154
	v_add_f32_e32 v212, v212, v213
	v_add_f32_e32 v230, v141, v212
	v_add_f32_e32 v141, v58, v59
	v_add_f32_e32 v154, v60, v61
	v_add_f32_e32 v212, v62, v63
	s_waitcnt lgkmcnt(6)
	v_mfma_f32_32x32x16_bf16 v[18:33], v[244:247], v[150:153], v[18:33]
	v_add_f32_e32 v213, v64, v65
	v_add_f32_e32 v141, v141, v154
	v_add_f32_e32 v212, v212, v213
	v_add_f32_e32 v141, v141, v212
	v_add_f32_e32 v230, v230, v141
	v_mfma_f32_32x32x16_bf16 v[2:17], v[248:251], v[150:153], v[2:17]
	v_add_f32_e32 v141, v34, v35
	v_add_f32_e32 v154, v36, v37
	v_add_f32_e32 v212, v38, v39
	v_add_f32_e32 v213, v40, v41
	v_add_f32_e32 v141, v141, v154
	v_add_f32_e32 v212, v212, v213
	s_waitcnt lgkmcnt(3)
	v_mfma_f32_32x32x16_bf16 v[18:33], v[208:211], v[142:145], v[18:33]
	v_add_f32_e32 v141, v141, v212
	v_add_f32_e32 v230, v230, v141
	v_add_f32_e32 v141, v42, v43
	v_add_f32_e32 v154, v44, v45
	v_add_f32_e32 v212, v46, v47
	v_mfma_f32_32x32x16_bf16 v[2:17], v[232:235], v[142:145], v[2:17]
	v_add_f32_e32 v213, v48, v49
	v_add_f32_e32 v141, v141, v154
	v_add_f32_e32 v212, v212, v213
	v_add_f32_e32 v141, v141, v212
	v_add_f32_e32 v230, v230, v141
	v_add_f32_e32 v135, v135, v230
	s_add_i32 s12, s12, 1
	s_add_i32 s16, s16, 64
	s_add_i32 s17, s12, 1
	s_cmp_ge_u32 s17, s66
	s_cbranch_scc1 .Lm3_final
	s_add_i32 s48, s16, 64
	s_lshl_b64 s[14:15], s[48:49], 1
	s_add_u32 s14, s6, s14
	s_addc_u32 s15, s7, s15
	global_load_dwordx4 v[78:81], v116, s[14:15]
	global_load_dwordx4 v[82:85], v118, s[14:15]
	s_add_i32 s48, s16, 0x80
	s_mul_i32 s14, s48, 0xc0
	s_mul_hi_u32 s13, s48, 0xc0
	s_add_u32 s14, s4, s14
	s_addc_u32 s15, s5, s13
	global_load_dwordx4 v[66:69], v0, s[14:15]
	global_load_dwordx4 v[70:73], v112, s[14:15]
	global_load_dwordx4 v[74:77], v114, s[14:15]
	s_waitcnt lgkmcnt(0)
	s_barrier
	ds_read_b128 v[208:211], v216 offset:0
	ds_read_b128 v[232:235], v216 offset:6656
	ds_read_b128 v[236:239], v216 offset:32
	ds_read_b128 v[240:243], v216 offset:6688
	ds_read_b128 v[244:247], v216 offset:64
	ds_read_b128 v[248:251], v216 offset:6720
	v_max3_f32 v120, v176, v177, v178
	v_max3_f32 v141, v179, v180, v181
	v_max3_f32 v154, v182, v183, v184
	v_max3_f32 v212, v185, v186, v187
	v_max3_f32 v120, v120, v188, v189
	v_max3_f32 v141, v141, v190, v191
	v_max3_f32 v154, v154, v192, v193
	v_max3_f32 v212, v212, v194, v195
	v_max3_f32 v120, v120, v196, v197
	v_max3_f32 v141, v141, v198, v199
	v_max3_f32 v154, v154, v200, v201
	v_max3_f32 v212, v212, v202, v203
	v_max3_f32 v120, v120, v204, v205
	v_max3_f32 v141, v141, v206, v207
	v_max3_f32 v120, v120, v141, v154
	v_max_f32_e32 v120, v120, v212
	v_mov_b32_e32 v141, v120
	s_nop 1
	v_permlane32_swap_b32_e32 v120, v141
	v_max_f32_e32 v120, v120, v141
	v_cmp_lt_f32_e32 vcc, 0x41000000, v120
	s_or_b64 vcc, vcc, s[20:21]
	s_cbranch_vccnz .Lm3_rare_o
;     ...
;     auto st_tile = [&](int buf) {
;         bf16_t* sK = (bf16_t*)(smem + buf * ATT_BUF); bf16_t* sV = (bf16_t*)(smem + buf * ATT_BUF + 13312); float* sC = (float*)(smem + buf * ATT_BUF + 22528);
; #pragma unroll
;     ...
;                 float mx = fmaxf(s4[0][0].x, s4[1][0].x);
; #pragma unroll
;                 for (int qd = 0; qd < 4; ++qd) {
;                     mx = fmaxf(fmaxf(mx, s4[0][qd].y), s4[1][qd].y);
;                     mx = fmaxf(fmaxf(mx, s4[0][qd].z), s4[1][qd].z);
;                     mx = fmaxf(fmaxf(mx, s4[0][qd].w), s4[1][qd].w);
;                     if (qd < 3) mx = fmaxf(fmaxf(mx, s4[0][qd + 1].x), s4[1][qd + 1].x);
;                 }
;                 mx = xhalf_max(mx);
;                 const float mn = fmaxf(m, mx), alpha = fexp2(m - mn);
;                 m = mn;
;                 f32x4 ps4 = {0.f, 0.f, 0.f, 0.f};
;                 const float nmn = -mn;
;                 const f32x4 nm4 = {nmn, nmn, nmn, nmn};
;                 if (__builtin_amdgcn_ballot_w64(alpha != 1.f) != 0) { o0 *= alpha; o1 *= alpha; }
; #pragma unroll
;                 for (int s2 = 0; s2 < 4; ++s2) {
;                     const int mt = s2 >> 1, s = s2 & 1;
;                     f32x4 da = s4[mt][2 * s] + nm4, db = s4[mt][2 * s + 1] + nm4;
;                     da.x = fexp2(da.x); da.y = fexp2(da.y); da.z = fexp2(da.z); da.w = fexp2(da.w);
;                     db.x = fexp2(db.x); db.y = fexp2(db.y); db.z = fexp2(db.z); db.w = fexp2(db.w);
;                     ps4 += da; ps4 += db;
;                     u32x4 pp;
;                     pp.x = pk2(da.x, da.y); pp.y = pk2(da.z, da.w); pp.z = pk2(db.x, db.y); pp.w = pk2(db.z, db.w);
;                     const bf16x8 pfr = __builtin_bit_cast(bf16x8, pp);
;                     const s16x4 a0 = *(const s16x4*)(sV + r * LS + 16 * s2 + 4 * h), a1 = *(const s16x4*)(sV + r * LS + 16 * s2 + 8 + 4 * h);
;                     const s16x4 b0 = *(const s16x4*)(sV + (32 + r) * LS + 16 * s2 + 4 * h), b1 = *(const s16x4*)(sV + (32 + r) * LS + 16 * s2 + 8 + 4 * h);
;                     const bf16x8 v0 = __builtin_shufflevector(a0, a1, 0, 1, 2, 3, 4, 5, 6, 7), v1 = __builtin_shufflevector(b0, b1, 0, 1, 2, 3, 4, 5, 6, 7);
;                     o0 = MFMA32(v0, pfr, o0);
;                     o1 = MFMA32(v1, pfr, o1);
;                 }
;                 lsum = lsum * alpha + ((ps4.x + ps4.y) + (ps4.z + ps4.w));
.Lm3_back_o:
	s_waitcnt lgkmcnt(4)
	v_mfma_f32_32x32x16_bf16 v[50:65], v[208:211], v[86:89], v[156:171]
	v_exp_f32_e32 v176, v176
	v_exp_f32_e32 v177, v177
	v_exp_f32_e32 v178, v178
	v_mfma_f32_32x32x16_bf16 v[34:49], v[232:235], v[86:89], v[156:171]
	ds_read_b128 v[208:211], v216 offset:96
	ds_read_b128 v[232:235], v216 offset:6752
	v_exp_f32_e32 v179, v179
	v_exp_f32_e32 v180, v180
	v_exp_f32_e32 v181, v181
	s_waitcnt lgkmcnt(4)
	v_mfma_f32_32x32x16_bf16 v[50:65], v[236:239], v[90:93], v[50:65]
	v_exp_f32_e32 v182, v182
	v_exp_f32_e32 v183, v183
	v_cvt_pk_bf16_f32 v142, v176, v177
	v_mfma_f32_32x32x16_bf16 v[34:49], v[240:243], v[90:93], v[34:49]
	ds_read_b128 v[236:239], v231 offset:36096
	ds_read_b128 v[240:243], v231 offset:40704
	v_cvt_pk_bf16_f32 v143, v178, v179
	v_cvt_pk_bf16_f32 v144, v180, v181
	v_cvt_pk_bf16_f32 v145, v182, v183
	v_exp_f32_e32 v184, v184
	s_waitcnt lgkmcnt(4)
	v_mfma_f32_32x32x16_bf16 v[50:65], v[244:247], v[94:97], v[50:65]
	v_exp_f32_e32 v185, v185
	v_exp_f32_e32 v186, v186
	v_exp_f32_e32 v187, v187
	v_mfma_f32_32x32x16_bf16 v[34:49], v[248:251], v[94:97], v[34:49]
	ds_read_b128 v[244:247], v216 offset:128
	ds_read_b128 v[248:251], v216 offset:6784
	v_exp_f32_e32 v188, v188
	v_exp_f32_e32 v189, v189
	v_exp_f32_e32 v190, v190
	s_waitcnt lgkmcnt(4)
	v_mfma_f32_32x32x16_bf16 v[50:65], v[208:211], v[98:101], v[50:65]
	v_exp_f32_e32 v191, v191
	v_cvt_pk_bf16_f32 v146, v184, v185
	v_cvt_pk_bf16_f32 v147, v186, v187
	v_cvt_pk_bf16_f32 v148, v188, v189
	v_mfma_f32_32x32x16_bf16 v[34:49], v[232:235], v[98:101], v[34:49]
	ds_read_b128 v[208:211], v231 offset:36128
	ds_read_b128 v[232:235], v231 offset:40736
	v_cvt_pk_bf16_f32 v149, v190, v191
	v_exp_f32_e32 v192, v192
	v_exp_f32_e32 v193, v193
	s_waitcnt lgkmcnt(4)
	v_mfma_f32_32x32x16_bf16 v[18:33], v[236:239], v[142:145], v[18:33]
	v_exp_f32_e32 v194, v194
	v_exp_f32_e32 v195, v195
	v_exp_f32_e32 v196, v196
	v_mfma_f32_32x32x16_bf16 v[2:17], v[240:243], v[142:145], v[2:17]
	ds_read_b128 v[236:239], v216 offset:160
	ds_read_b128 v[240:243], v216 offset:6816
	v_exp_f32_e32 v197, v197
	v_exp_f32_e32 v198, v198
	v_exp_f32_e32 v199, v199
	s_waitcnt lgkmcnt(4)
	v_mfma_f32_32x32x16_bf16 v[50:65], v[244:247], v[102:105], v[50:65]
	v_cvt_pk_bf16_f32 v150, v192, v193
	v_cvt_pk_bf16_f32 v151, v194, v195
	v_cvt_pk_bf16_f32 v152, v196, v197
	v_cvt_pk_bf16_f32 v153, v198, v199
	v_exp_f32_e32 v200, v200
	v_mfma_f32_32x32x16_bf16 v[34:49], v[248:251], v[102:105], v[34:49]
	s_waitcnt vmcnt(0)
	ds_write2_b64 v130, v[78:79], v[80:81] offset1:2
	ds_read_b128 v[244:247], v231 offset:36160
	ds_read_b128 v[248:251], v231 offset:40768
	v_exp_f32_e32 v201, v201
	v_exp_f32_e32 v202, v202
	v_exp_f32_e32 v203, v203
	s_waitcnt lgkmcnt(5)
	v_mfma_f32_32x32x16_bf16 v[18:33], v[208:211], v[146:149], v[18:33]
	ds_write2_b64 v132, v[82:83], v[84:85] offset1:2
	v_exp_f32_e32 v204, v204
	v_exp_f32_e32 v205, v205
	v_mfma_f32_32x32x16_bf16 v[2:17], v[232:235], v[146:149], v[2:17]
	ds_write_b128 v127, v[66:69] offset:22784
	ds_read_b128 v[208:211], v231 offset:36192
	ds_read_b128 v[232:235], v231 offset:40800
	v_exp_f32_e32 v206, v206
	v_exp_f32_e32 v207, v207
	v_cvt_pk_bf16_f32 v142, v200, v201
	v_cvt_pk_bf16_f32 v143, v202, v203
	s_waitcnt lgkmcnt(7)
	v_mfma_f32_32x32x16_bf16 v[50:65], v[236:239], v[106:109], v[50:65]
	ds_write_b128 v128, v[70:73] offset:22784
	v_cvt_pk_bf16_f32 v144, v204, v205
	v_cvt_pk_bf16_f32 v145, v206, v207
	v_add_f32_e32 v141, v176, v177
	v_add_f32_e32 v154, v178, v179
	v_add_f32_e32 v212, v180, v181
	v_add_f32_e32 v213, v182, v183
	v_mfma_f32_32x32x16_bf16 v[34:49], v[240:243], v[106:109], v[34:49]
	ds_write_b128 v129, v[74:77] offset:22784
	v_add_f32_e32 v141, v141, v154
	v_add_f32_e32 v212, v212, v213
	v_add_f32_e32 v230, v141, v212
	v_add_f32_e32 v141, v184, v185
	v_add_f32_e32 v154, v186, v187
	v_add_f32_e32 v212, v188, v189
	s_waitcnt lgkmcnt(6)
	v_mfma_f32_32x32x16_bf16 v[18:33], v[244:247], v[150:153], v[18:33]
	v_add_f32_e32 v213, v190, v191
	v_add_f32_e32 v141, v141, v154
	v_add_f32_e32 v212, v212, v213
	v_add_f32_e32 v141, v141, v212
	v_add_f32_e32 v230, v230, v141
	v_mfma_f32_32x32x16_bf16 v[2:17], v[248:251], v[150:153], v[2:17]
	v_add_f32_e32 v141, v192, v193
	v_add_f32_e32 v154, v194, v195
	v_add_f32_e32 v212, v196, v197
	v_add_f32_e32 v213, v198, v199
	v_add_f32_e32 v141, v141, v154
	v_add_f32_e32 v212, v212, v213
	s_waitcnt lgkmcnt(2)
	v_mfma_f32_32x32x16_bf16 v[18:33], v[208:211], v[142:145], v[18:33]
	v_add_f32_e32 v141, v141, v212
	v_add_f32_e32 v230, v230, v141
	v_add_f32_e32 v141, v200, v201
	v_add_f32_e32 v154, v202, v203
	v_add_f32_e32 v212, v204, v205
	v_mfma_f32_32x32x16_bf16 v[2:17], v[232:235], v[142:145], v[2:17]
	v_add_f32_e32 v213, v206, v207
	v_add_f32_e32 v141, v141, v154
	v_add_f32_e32 v212, v212, v213
	v_add_f32_e32 v141, v141, v212
	v_add_f32_e32 v230, v230, v141
	v_add_f32_e32 v135, v135, v230
	s_add_i32 s12, s12, 1
	s_add_i32 s16, s16, 64
	s_branch .Lm3_even
